# static priority raise: one s_setprio 1 at kernel entry for waves 4-7 (younger half), no per-segment flips
# baseline (speedup 1.0000x reference)
; #define BOTH(k) (IN(k) && IN((k) + 1))
; #define GRID_BAR() do { if (N_LAUNCHES != PER_PHASE) xcd_barrier(bar); } while (0)
; template <int ROT>
; __device__ __forceinline__ void gu_absmax(Frame& F, int s_lo, int s_hi) {
;     const int gw = F.vcu * 8 + F.wave, NGW = F.G * 8, lane = (F.tid & 63), kr = lane >> 4, nq = lane & 15;
;     for (int sidx = s_lo + gw; sidx < s_hi; sidx += NGW) {
;         int q, r; if (sidx < GU_STRIPS) { q = sidx / 1376; r = sidx % 1376; } else if (sidx < GU_STRIPS_ALL) { q = 4; r = sidx - GU_STRIPS; } else { q = 5; r = sidx - GU_STRIPS_ALL; }
;         const int nbk = q < 4 ? 172 : 64, kb = r / nbk, nb = r % nbk, rowlen = q < 4 ? FF : DM, ktot = q < 4 ? DM : FF;
;         const float* W = q == 0 ? INP(2) : q == 1 ? INP(3) : q == 2 ? INP(18) : q == 3 ? INP(19) : q == 4 ? INP(20) : INP(4); const float* gain = q < 2 ? INP(1) : (q < 4 ? INP(17) : nullptr);
;         unsigned* cmax = (unsigned*)(F.ws + WS_CTL + CTL_CMAX) + (q < 4 ? (q >> 1) * NGU : 2 * NGU + (q - 4) * DM);
;         const int n = 64 * nb + 4 * nq;
; __global__ void __launch_bounds__(512, 2) mk_fwd(Args args) {
;     ...
;     const int lo = args.ph_lo, hi = args.ph_hi;
;     ...
;     u64* racc1 = (u64*)(ws + WS_CTL + CTL_RACC); u64* racc2 = racc1 + M; u64* racc3 = racc2 + M;
;     bf16_t* actb = (bf16_t*)(ws + WS_ACTB); bf16_t* hid = (bf16_t*)(ws + WS_HID);
;     static_assert(N_LAUNCHES == 1, "phases 0 and 6 contain an in-phase grid barrier");
;     if (IN(0)) { gu_absmax<ROT2>(F, GU_STRIPS, GU_STRIPS_ALL); gu_absmax<ROT1>(F, GU_STRIPS_ALL, GU_STRIPS_ALL + 1408); gu_absmax<0>(F, 2752, GU_STRIPS); GRID_BAR(); p0_prologue(F); if (BOTH(0)) GRID_BAR(); }
.LBB0_8:
	s_or_b64 exec, exec, s[2:3]
	s_load_dwordx2 s[72:73], s[0:1], 0xc0
	s_lshr_b32 s68, s70, 6
	s_cmp_lt_u32 s68, 4
	s_cbranch_scc1 .Lmy_prio_done
	s_setprio 1
.Lmy_prio_done:
	v_writelane_b32 v246, s60, 5
	s_waitcnt lgkmcnt(0)
	s_cmp_lt_i32 s72, 1
	s_cselect_b64 s[0:1], -1, 0
	s_cmp_gt_i32 s73, 0
	s_cselect_b64 s[2:3], -1, 0
	s_and_b64 s[0:1], s[0:1], s[2:3]
	s_andn2_b64 vcc, exec, s[0:1]
	v_writelane_b32 v246, s61, 6
	s_cbranch_vccnz .LBB0_1159
	s_lshl_b32 s34, s65, 3
	s_add_i32 s10, s68, s34
	s_lshl_b32 s12, s71, 3
	v_and_b32_e32 v1, 63, v0
	s_add_i32 s11, s10, 0x1580
	s_cmpk_gt_i32 s11, 0x1aff
	v_and_b32_e32 v72, 16, v0
	v_cmp_gt_u32_e64 s[2:3], 16, v1
	s_cbranch_scc1 .LBB0_46
	v_lshlrev_b32_e32 v2, 2, v0
	v_and_b32_e32 v73, 60, v2
	v_lshrrev_b32_e32 v2, 3, v0
	v_and_b32_e32 v74, 6, v2
	v_mbcnt_lo_u32_b32 v2, -1, 0
	v_mbcnt_hi_u32_b32 v2, -1, v2
	v_and_b32_e32 v4, 64, v2
	v_xor_b32_e32 v3, 16, v2
	v_add_u32_e32 v5, 64, v4
	v_cmp_lt_i32_e32 vcc, v3, v5
	s_add_u32 s13, s78, 0x80000
	s_mov_b32 s1, 0
	v_cndmask_b32_e32 v3, v2, v3, vcc
	v_lshlrev_b32_e32 v75, 2, v3
	v_xor_b32_e32 v3, 32, v2
	v_cmp_lt_i32_e32 vcc, v3, v5
	v_cmp_eq_u32_e64 s[4:5], 0, v72
	s_addc_u32 s18, s79, 0
	v_cndmask_b32_e32 v2, v2, v3, vcc
	v_lshlrev_b32_e32 v76, 2, v2
	v_or_b32_e32 v2, v4, v74
	v_lshlrev_b32_e32 v77, 2, v2
	v_or_b32_e32 v78, 4, v77
	v_or_b32_e32 v79, 32, v77
	v_or_b32_e32 v80, 36, v77
	v_or_b32_e32 v81, 64, v77
	v_or_b32_e32 v82, 0x44, v77
	v_or_b32_e32 v83, 0x60, v77
	v_or_b32_e32 v84, 0x64, v77
	v_or_b32_e32 v85, 0x80, v77
	v_or_b32_e32 v86, 0x84, v77
	v_or_b32_e32 v87, 0xa0, v77
	v_or_b32_e32 v88, 0xa4, v77
	v_or_b32_e32 v89, 0xc0, v77
	v_or_b32_e32 v90, 0xc4, v77
	v_or_b32_e32 v91, 0xe0, v77
	v_or_b32_e32 v92, 0xe4, v77
	s_mov_b32 s19, 0x27c08
	s_movk_i32 s20, 0x1000
	s_mov_b64 s[14:15], 0x100
	v_mov_b32_e32 v93, 0x7c
	s_branch .LBB0_12
